# attention loop: 8 LDS read buffers, fragment prefetch distance 7 MFMA slots (was 7 buffers / distance 6), on top of v22
# speedup vs baseline: 1.0153x; 1.0153x over previous
.Lattn_fx_loop:
	ds_read_b128 v[188:191], v187 offset:22528
	ds_read_b128 v[168:171], v187 offset:22560
	ds_read_b128 v[220:223], v187 offset:22592
	s_waitcnt lgkmcnt(6)
	v_mfma_f32_32x32x16_bf16 v[16:31], v[128:131], v[112:115], v[16:31]
	ds_read_b128 v[224:227], v187 offset:22624
	s_waitcnt vmcnt(0)
	ds_write_b128 v211, v[176:179] offset:45056
	s_and_saveexec_b64 s[42:43], s[36:37]
	s_cbranch_execz .Lattn_fx_w0
	ds_write_b128 v186, v[172:175] offset:45056
.Lattn_fx_w0:
	s_or_b64 exec, exec, s[42:43]
	ds_write_b128 v208, v[180:183] offset:58368
	v_exp_f32_e32 v48, v48
	v_exp_f32_e32 v49, v49
	v_exp_f32_e32 v50, v50
	s_waitcnt lgkmcnt(8)
	v_mfma_f32_32x32x16_bf16 v[32:47], v[132:135], v[112:115], v[32:47]
	ds_read_b128 v[128:131], v187 offset:22656
	global_load_dwordx4 v[176:179], v212, s[6:7]
	s_and_saveexec_b64 s[42:43], s[36:37]
	s_cbranch_execz .Lattn_fx_g1
	global_load_dwordx4 v[172:175], v214, s[6:7]
.Lattn_fx_g1:
	s_or_b64 exec, exec, s[42:43]
	global_load_dwordx4 v[180:183], v204, s[40:41]
	s_add_u32 s6, s6, 0x18000
	s_addc_u32 s7, s7, 0
	s_add_u32 s40, s40, 0x80
	s_addc_u32 s41, s41, 0
	v_exp_f32_e32 v51, v51
	v_exp_f32_e32 v52, v52
	v_exp_f32_e32 v53, v53
	s_waitcnt lgkmcnt(8)
	v_mfma_f32_32x32x16_bf16 v[16:31], v[136:139], v[116:119], v[16:31]
	ds_read_b128 v[132:135], v187 offset:22688
	v_exp_f32_e32 v54, v54
	v_exp_f32_e32 v55, v55
	v_cvt_pk_bf16_f32 v120, v48, v49
	v_cvt_pk_bf16_f32 v121, v50, v51
	s_waitcnt lgkmcnt(8)
	v_mfma_f32_32x32x16_bf16 v[32:47], v[140:143], v[116:119], v[32:47]
	ds_read_b128 v[136:139], v209 offset:13376
	v_cvt_pk_bf16_f32 v122, v52, v53
	v_cvt_pk_bf16_f32 v123, v54, v55
	v_exp_f32_e32 v56, v56
	v_exp_f32_e32 v57, v57
	s_waitcnt lgkmcnt(8)
	v_mfma_f32_32x32x16_bf16 v[96:111], v[188:191], v[164:167], v[0:15]
	ds_read_b128 v[140:143], v209 offset:17984
	v_exp_f32_e32 v58, v58
	v_exp_f32_e32 v59, v59
	v_add_f32_e32 v48, v64, v48
	v_add_f32_e32 v244, v244, v48
	s_waitcnt lgkmcnt(8)
	v_mfma_f32_32x32x16_bf16 v[96:111], v[168:171], v[144:147], v[96:111]
	ds_read_b128 v[188:191], v187 offset:29184
	v_exp_f32_e32 v60, v60
	v_exp_f32_e32 v61, v61
	v_add_f32_e32 v49, v65, v49
	v_add_f32_e32 v245, v245, v49
	s_waitcnt lgkmcnt(8)
	v_mfma_f32_32x32x16_bf16 v[96:111], v[220:223], v[148:151], v[96:111]
	ds_read_b128 v[168:171], v187 offset:29216
	v_exp_f32_e32 v62, v62
	v_exp_f32_e32 v63, v63
	v_add_f32_e32 v50, v66, v50
	v_add_f32_e32 v242, v242, v50
	s_waitcnt lgkmcnt(8)
	v_mfma_f32_32x32x16_bf16 v[96:111], v[224:227], v[152:155], v[96:111]
	ds_read_b128 v[220:223], v187 offset:29248
	v_cvt_pk_bf16_f32 v124, v56, v57
	v_cvt_pk_bf16_f32 v125, v58, v59
	v_cvt_pk_bf16_f32 v126, v60, v61
	v_cvt_pk_bf16_f32 v127, v62, v63
	v_add_f32_e32 v51, v67, v51
	v_add_f32_e32 v243, v243, v51
	s_waitcnt lgkmcnt(6)
	v_mfma_f32_32x32x16_bf16 v[96:111], v[128:131], v[156:159], v[96:111]
	ds_read_b128 v[224:227], v209 offset:13408
	v_add_f32_e32 v52, v68, v52
	v_add_f32_e32 v240, v240, v52
	v_add_f32_e32 v53, v69, v53
	v_add_f32_e32 v241, v241, v53
	v_add_f32_e32 v54, v70, v54
	v_add_f32_e32 v238, v238, v54
	s_waitcnt lgkmcnt(6)
	v_mfma_f32_32x32x16_bf16 v[96:111], v[132:135], v[160:163], v[96:111]
	ds_read_b128 v[128:131], v209 offset:18016
	v_add_f32_e32 v55, v71, v55
	v_add_f32_e32 v239, v239, v55
	v_add_f32_e32 v56, v72, v56
	v_add_f32_e32 v236, v236, v56
	v_add_f32_e32 v57, v73, v57
	v_add_f32_e32 v237, v237, v57
	s_waitcnt lgkmcnt(6)
	v_mfma_f32_32x32x16_bf16 v[16:31], v[136:139], v[120:123], v[16:31]
	ds_read_b128 v[132:135], v187 offset:29280
	v_add_f32_e32 v58, v74, v58
	v_add_f32_e32 v234, v234, v58
	v_add_f32_e32 v59, v75, v59
	v_add_f32_e32 v235, v235, v59
	v_add_f32_e32 v60, v76, v60
	v_add_f32_e32 v232, v232, v60
	s_waitcnt lgkmcnt(6)
	v_mfma_f32_32x32x16_bf16 v[32:47], v[140:143], v[120:123], v[32:47]
	ds_read_b128 v[136:139], v187 offset:29312
	v_add_f32_e32 v61, v77, v61
	v_add_f32_e32 v233, v233, v61
	v_add_f32_e32 v62, v78, v62
	v_add_f32_e32 v230, v230, v62
	s_waitcnt lgkmcnt(6)
	v_mfma_f32_32x32x16_bf16 v[80:95], v[188:191], v[164:167], v[0:15]
	ds_read_b128 v[140:143], v187 offset:29344
	v_exp_f32_e32 v96, v96
	v_exp_f32_e32 v97, v97
	v_exp_f32_e32 v98, v98
	s_waitcnt lgkmcnt(6)
	v_mfma_f32_32x32x16_bf16 v[80:95], v[168:171], v[144:147], v[80:95]
	ds_read_b128 v[188:191], v209 offset:35840
	v_exp_f32_e32 v99, v99
	v_exp_f32_e32 v100, v100
	v_exp_f32_e32 v101, v101
	s_waitcnt lgkmcnt(6)
	v_mfma_f32_32x32x16_bf16 v[80:95], v[220:223], v[148:151], v[80:95]
	ds_read_b128 v[168:171], v209 offset:40448
	v_exp_f32_e32 v102, v102
	v_exp_f32_e32 v103, v103
	v_cvt_pk_bf16_f32 v112, v96, v97
	v_cvt_pk_bf16_f32 v113, v98, v99
	s_waitcnt lgkmcnt(6)
	v_mfma_f32_32x32x16_bf16 v[16:31], v[224:227], v[124:127], v[16:31]
	ds_read_b128 v[220:223], v209 offset:35872
	v_cvt_pk_bf16_f32 v114, v100, v101
	v_cvt_pk_bf16_f32 v115, v102, v103
	v_exp_f32_e32 v104, v104
	v_exp_f32_e32 v105, v105
	s_waitcnt lgkmcnt(6)
	v_mfma_f32_32x32x16_bf16 v[32:47], v[128:131], v[124:127], v[32:47]
	ds_read_b128 v[224:227], v209 offset:40480
	v_exp_f32_e32 v106, v106
	v_exp_f32_e32 v107, v107
	v_exp_f32_e32 v108, v108
	s_waitcnt lgkmcnt(6)
	v_mfma_f32_32x32x16_bf16 v[80:95], v[132:135], v[152:155], v[80:95]
	v_exp_f32_e32 v109, v109
	v_exp_f32_e32 v110, v110
	v_exp_f32_e32 v111, v111
	s_waitcnt lgkmcnt(5)
	v_mfma_f32_32x32x16_bf16 v[80:95], v[136:139], v[156:159], v[80:95]
	v_cvt_pk_bf16_f32 v116, v104, v105
	v_cvt_pk_bf16_f32 v117, v106, v107
	v_cvt_pk_bf16_f32 v118, v108, v109
	v_cvt_pk_bf16_f32 v119, v110, v111
	s_waitcnt lgkmcnt(4)
	v_mfma_f32_32x32x16_bf16 v[80:95], v[140:143], v[160:163], v[80:95]
	v_add_f32_e32 v63, v79, v63
	v_add_f32_e32 v231, v231, v63
	s_waitcnt lgkmcnt(4)
	s_barrier
	ds_read_b128 v[128:131], v187 offset:45056
	ds_read_b128 v[132:135], v187 offset:45088
	ds_read_b128 v[136:139], v187 offset:45120
	s_waitcnt lgkmcnt(6)
	v_mfma_f32_32x32x16_bf16 v[16:31], v[188:191], v[112:115], v[16:31]
	ds_read_b128 v[140:143], v187 offset:45152
	s_waitcnt vmcnt(0)
	ds_write_b128 v211, v[176:179] offset:0
	s_and_saveexec_b64 s[42:43], s[36:37]
	s_cbranch_execz .Lattn_fx_w2
	ds_write_b128 v186, v[172:175] offset:0
.Lattn_fx_w2:
	s_or_b64 exec, exec, s[42:43]
	ds_write_b128 v208, v[180:183] offset:13312
	v_exp_f32_e32 v80, v80
	v_exp_f32_e32 v81, v81
	v_exp_f32_e32 v82, v82
	s_waitcnt lgkmcnt(8)
	v_mfma_f32_32x32x16_bf16 v[32:47], v[168:171], v[112:115], v[32:47]
	ds_read_b128 v[188:191], v187 offset:45184
	global_load_dwordx4 v[176:179], v212, s[6:7]
	s_and_saveexec_b64 s[42:43], s[36:37]
	s_cbranch_execz .Lattn_fx_g3
	global_load_dwordx4 v[172:175], v214, s[6:7]
.Lattn_fx_g3:
	s_or_b64 exec, exec, s[42:43]
	global_load_dwordx4 v[180:183], v204, s[40:41]
	s_add_u32 s6, s6, 0x18000
	s_addc_u32 s7, s7, 0
	s_add_u32 s40, s40, 0x80
	s_addc_u32 s41, s41, 0
	v_exp_f32_e32 v83, v83
	v_exp_f32_e32 v84, v84
	v_exp_f32_e32 v85, v85
	s_waitcnt lgkmcnt(8)
	v_mfma_f32_32x32x16_bf16 v[16:31], v[220:223], v[116:119], v[16:31]
	ds_read_b128 v[168:171], v187 offset:45216
	v_exp_f32_e32 v86, v86
	v_exp_f32_e32 v87, v87
	v_cvt_pk_bf16_f32 v120, v80, v81
	v_cvt_pk_bf16_f32 v121, v82, v83
	s_waitcnt lgkmcnt(8)
	v_mfma_f32_32x32x16_bf16 v[32:47], v[224:227], v[116:119], v[32:47]
	ds_read_b128 v[220:223], v209 offset:35904
	v_cvt_pk_bf16_f32 v122, v84, v85
	v_cvt_pk_bf16_f32 v123, v86, v87
	v_exp_f32_e32 v88, v88
	v_exp_f32_e32 v89, v89
	s_waitcnt lgkmcnt(8)
	v_mfma_f32_32x32x16_bf16 v[64:79], v[128:131], v[164:167], v[0:15]
	ds_read_b128 v[224:227], v209 offset:40512
	v_exp_f32_e32 v90, v90
	v_exp_f32_e32 v91, v91
	v_add_f32_e32 v80, v96, v80
	v_add_f32_e32 v244, v244, v80
	s_waitcnt lgkmcnt(8)
	v_mfma_f32_32x32x16_bf16 v[64:79], v[132:135], v[144:147], v[64:79]
	ds_read_b128 v[128:131], v187 offset:51712
	v_exp_f32_e32 v92, v92
	v_exp_f32_e32 v93, v93
	v_add_f32_e32 v81, v97, v81
	v_add_f32_e32 v245, v245, v81
	s_waitcnt lgkmcnt(8)
	v_mfma_f32_32x32x16_bf16 v[64:79], v[136:139], v[148:151], v[64:79]
	ds_read_b128 v[132:135], v187 offset:51744
	v_exp_f32_e32 v94, v94
	v_exp_f32_e32 v95, v95
	v_add_f32_e32 v82, v98, v82
	v_add_f32_e32 v242, v242, v82
	s_waitcnt lgkmcnt(8)
	v_mfma_f32_32x32x16_bf16 v[64:79], v[140:143], v[152:155], v[64:79]
	ds_read_b128 v[136:139], v187 offset:51776
	v_cvt_pk_bf16_f32 v124, v88, v89
	v_cvt_pk_bf16_f32 v125, v90, v91
	v_cvt_pk_bf16_f32 v126, v92, v93
	v_cvt_pk_bf16_f32 v127, v94, v95
	v_add_f32_e32 v83, v99, v83
	v_add_f32_e32 v243, v243, v83
	s_waitcnt lgkmcnt(6)
	v_mfma_f32_32x32x16_bf16 v[64:79], v[188:191], v[156:159], v[64:79]
	ds_read_b128 v[140:143], v209 offset:35936
	v_add_f32_e32 v84, v100, v84
	v_add_f32_e32 v240, v240, v84
	v_add_f32_e32 v85, v101, v85
	v_add_f32_e32 v241, v241, v85
	v_add_f32_e32 v86, v102, v86
	v_add_f32_e32 v238, v238, v86
	s_waitcnt lgkmcnt(6)
	v_mfma_f32_32x32x16_bf16 v[64:79], v[168:171], v[160:163], v[64:79]
	ds_read_b128 v[188:191], v209 offset:40544
	v_add_f32_e32 v87, v103, v87
	v_add_f32_e32 v239, v239, v87
	v_add_f32_e32 v88, v104, v88
	v_add_f32_e32 v236, v236, v88
	v_add_f32_e32 v89, v105, v89
	v_add_f32_e32 v237, v237, v89
	s_waitcnt lgkmcnt(6)
	v_mfma_f32_32x32x16_bf16 v[16:31], v[220:223], v[120:123], v[16:31]
	ds_read_b128 v[168:171], v187 offset:51808
	v_add_f32_e32 v90, v106, v90
	v_add_f32_e32 v234, v234, v90
	v_add_f32_e32 v91, v107, v91
	v_add_f32_e32 v235, v235, v91
	v_add_f32_e32 v92, v108, v92
	v_add_f32_e32 v232, v232, v92
	s_waitcnt lgkmcnt(6)
	v_mfma_f32_32x32x16_bf16 v[32:47], v[224:227], v[120:123], v[32:47]
	ds_read_b128 v[220:223], v187 offset:51840
	v_add_f32_e32 v93, v109, v93
	v_add_f32_e32 v233, v233, v93
	v_add_f32_e32 v94, v110, v94
	v_add_f32_e32 v230, v230, v94
	s_waitcnt lgkmcnt(6)
	v_mfma_f32_32x32x16_bf16 v[48:63], v[128:131], v[164:167], v[0:15]
	ds_read_b128 v[224:227], v187 offset:51872
	v_exp_f32_e32 v64, v64
	v_exp_f32_e32 v65, v65
	v_exp_f32_e32 v66, v66
	s_waitcnt lgkmcnt(6)
	v_mfma_f32_32x32x16_bf16 v[48:63], v[132:135], v[144:147], v[48:63]
	ds_read_b128 v[128:131], v209 offset:58368
	v_exp_f32_e32 v67, v67
	v_exp_f32_e32 v68, v68
	v_exp_f32_e32 v69, v69
	s_waitcnt lgkmcnt(6)
	v_mfma_f32_32x32x16_bf16 v[48:63], v[136:139], v[148:151], v[48:63]
	ds_read_b128 v[132:135], v209 offset:62976
	v_exp_f32_e32 v70, v70
	v_exp_f32_e32 v71, v71
	v_cvt_pk_bf16_f32 v112, v64, v65
	v_cvt_pk_bf16_f32 v113, v66, v67
	s_waitcnt lgkmcnt(6)
	v_mfma_f32_32x32x16_bf16 v[16:31], v[140:143], v[124:127], v[16:31]
	ds_read_b128 v[136:139], v209 offset:58400
	v_cvt_pk_bf16_f32 v114, v68, v69
	v_cvt_pk_bf16_f32 v115, v70, v71
	v_exp_f32_e32 v72, v72
	v_exp_f32_e32 v73, v73
	s_waitcnt lgkmcnt(6)
	v_mfma_f32_32x32x16_bf16 v[32:47], v[188:191], v[124:127], v[32:47]
	ds_read_b128 v[140:143], v209 offset:63008
	v_exp_f32_e32 v74, v74
	v_exp_f32_e32 v75, v75
	v_exp_f32_e32 v76, v76
	s_waitcnt lgkmcnt(6)
	v_mfma_f32_32x32x16_bf16 v[48:63], v[168:171], v[152:155], v[48:63]
	v_exp_f32_e32 v77, v77
	v_exp_f32_e32 v78, v78
	v_exp_f32_e32 v79, v79
	s_waitcnt lgkmcnt(5)
	v_mfma_f32_32x32x16_bf16 v[48:63], v[220:223], v[156:159], v[48:63]
	v_cvt_pk_bf16_f32 v116, v72, v73
	v_cvt_pk_bf16_f32 v117, v74, v75
	v_cvt_pk_bf16_f32 v118, v76, v77
	v_cvt_pk_bf16_f32 v119, v78, v79
	s_waitcnt lgkmcnt(4)
	v_mfma_f32_32x32x16_bf16 v[48:63], v[224:227], v[160:163], v[48:63]
	v_add_f32_e32 v95, v111, v95
	v_add_f32_e32 v231, v231, v95
	s_waitcnt lgkmcnt(4)
	s_barrier
	ds_read_b128 v[188:191], v187 offset:0
	ds_read_b128 v[168:171], v187 offset:32
	ds_read_b128 v[220:223], v187 offset:64
	s_waitcnt lgkmcnt(6)
	v_mfma_f32_32x32x16_bf16 v[16:31], v[128:131], v[112:115], v[16:31]
	ds_read_b128 v[224:227], v187 offset:96
	s_waitcnt vmcnt(0)
	ds_write_b128 v211, v[176:179] offset:22528
	s_and_saveexec_b64 s[42:43], s[36:37]
	s_cbranch_execz .Lattn_fx_w4
	ds_write_b128 v186, v[172:175] offset:22528
.Lattn_fx_w4:
	s_or_b64 exec, exec, s[42:43]
	ds_write_b128 v208, v[180:183] offset:35840
	v_exp_f32_e32 v48, v48
	v_exp_f32_e32 v49, v49
	v_exp_f32_e32 v50, v50
	s_waitcnt lgkmcnt(8)
	v_mfma_f32_32x32x16_bf16 v[32:47], v[132:135], v[112:115], v[32:47]
	ds_read_b128 v[128:131], v187 offset:128
	global_load_dwordx4 v[176:179], v212, s[6:7]
	s_and_saveexec_b64 s[42:43], s[36:37]
	s_cbranch_execz .Lattn_fx_g5
	global_load_dwordx4 v[172:175], v214, s[6:7]
.Lattn_fx_g5:
	s_or_b64 exec, exec, s[42:43]
	global_load_dwordx4 v[180:183], v204, s[40:41]
	s_add_u32 s6, s6, 0x18000
	s_addc_u32 s7, s7, 0
	s_add_u32 s40, s40, 0x80
	s_addc_u32 s41, s41, 0
	v_exp_f32_e32 v51, v51
	v_exp_f32_e32 v52, v52
	v_exp_f32_e32 v53, v53
	s_waitcnt lgkmcnt(8)
	v_mfma_f32_32x32x16_bf16 v[16:31], v[136:139], v[116:119], v[16:31]
	ds_read_b128 v[132:135], v187 offset:160
	v_exp_f32_e32 v54, v54
	v_exp_f32_e32 v55, v55
	v_cvt_pk_bf16_f32 v120, v48, v49
	v_cvt_pk_bf16_f32 v121, v50, v51
	s_waitcnt lgkmcnt(8)
	v_mfma_f32_32x32x16_bf16 v[32:47], v[140:143], v[116:119], v[32:47]
	ds_read_b128 v[136:139], v209 offset:58432
	v_cvt_pk_bf16_f32 v122, v52, v53
	v_cvt_pk_bf16_f32 v123, v54, v55
	v_exp_f32_e32 v56, v56
	v_exp_f32_e32 v57, v57
	s_waitcnt lgkmcnt(8)
	v_mfma_f32_32x32x16_bf16 v[96:111], v[188:191], v[164:167], v[0:15]
	ds_read_b128 v[140:143], v209 offset:63040
	v_exp_f32_e32 v58, v58
	v_exp_f32_e32 v59, v59
	v_add_f32_e32 v48, v64, v48
	v_add_f32_e32 v244, v244, v48
	s_waitcnt lgkmcnt(8)
	v_mfma_f32_32x32x16_bf16 v[96:111], v[168:171], v[144:147], v[96:111]
	ds_read_b128 v[188:191], v187 offset:6656
	v_exp_f32_e32 v60, v60
	v_exp_f32_e32 v61, v61
	v_add_f32_e32 v49, v65, v49
	v_add_f32_e32 v245, v245, v49
	s_waitcnt lgkmcnt(8)
	v_mfma_f32_32x32x16_bf16 v[96:111], v[220:223], v[148:151], v[96:111]
	ds_read_b128 v[168:171], v187 offset:6688
	v_exp_f32_e32 v62, v62
	v_exp_f32_e32 v63, v63
	v_add_f32_e32 v50, v66, v50
	v_add_f32_e32 v242, v242, v50
	s_waitcnt lgkmcnt(8)
	v_mfma_f32_32x32x16_bf16 v[96:111], v[224:227], v[152:155], v[96:111]
	ds_read_b128 v[220:223], v187 offset:6720
	v_cvt_pk_bf16_f32 v124, v56, v57
	v_cvt_pk_bf16_f32 v125, v58, v59
	v_cvt_pk_bf16_f32 v126, v60, v61
	v_cvt_pk_bf16_f32 v127, v62, v63
	v_add_f32_e32 v51, v67, v51
	v_add_f32_e32 v243, v243, v51
	s_waitcnt lgkmcnt(6)
	v_mfma_f32_32x32x16_bf16 v[96:111], v[128:131], v[156:159], v[96:111]
	ds_read_b128 v[224:227], v209 offset:58464
	v_add_f32_e32 v52, v68, v52
	v_add_f32_e32 v240, v240, v52
	v_add_f32_e32 v53, v69, v53
	v_add_f32_e32 v241, v241, v53
	v_add_f32_e32 v54, v70, v54
	v_add_f32_e32 v238, v238, v54
	s_waitcnt lgkmcnt(6)
	v_mfma_f32_32x32x16_bf16 v[96:111], v[132:135], v[160:163], v[96:111]
	ds_read_b128 v[128:131], v209 offset:63072
	v_add_f32_e32 v55, v71, v55
	v_add_f32_e32 v239, v239, v55
	v_add_f32_e32 v56, v72, v56
	v_add_f32_e32 v236, v236, v56
	v_add_f32_e32 v57, v73, v57
	v_add_f32_e32 v237, v237, v57
	s_waitcnt lgkmcnt(6)
	v_mfma_f32_32x32x16_bf16 v[16:31], v[136:139], v[120:123], v[16:31]
	ds_read_b128 v[132:135], v187 offset:6752
	v_add_f32_e32 v58, v74, v58
	v_add_f32_e32 v234, v234, v58
	v_add_f32_e32 v59, v75, v59
	v_add_f32_e32 v235, v235, v59
	v_add_f32_e32 v60, v76, v60
	v_add_f32_e32 v232, v232, v60
	s_waitcnt lgkmcnt(6)
	v_mfma_f32_32x32x16_bf16 v[32:47], v[140:143], v[120:123], v[32:47]
	ds_read_b128 v[136:139], v187 offset:6784
	v_add_f32_e32 v61, v77, v61
	v_add_f32_e32 v233, v233, v61
	v_add_f32_e32 v62, v78, v62
	v_add_f32_e32 v230, v230, v62
	s_waitcnt lgkmcnt(6)
	v_mfma_f32_32x32x16_bf16 v[80:95], v[188:191], v[164:167], v[0:15]
	ds_read_b128 v[140:143], v187 offset:6816
	v_exp_f32_e32 v96, v96
	v_exp_f32_e32 v97, v97
	v_exp_f32_e32 v98, v98
	s_waitcnt lgkmcnt(6)
	v_mfma_f32_32x32x16_bf16 v[80:95], v[168:171], v[144:147], v[80:95]
	ds_read_b128 v[188:191], v209 offset:13312
	v_exp_f32_e32 v99, v99
	v_exp_f32_e32 v100, v100
	v_exp_f32_e32 v101, v101
	s_waitcnt lgkmcnt(6)
	v_mfma_f32_32x32x16_bf16 v[80:95], v[220:223], v[148:151], v[80:95]
	ds_read_b128 v[168:171], v209 offset:17920
	v_exp_f32_e32 v102, v102
	v_exp_f32_e32 v103, v103
	v_cvt_pk_bf16_f32 v112, v96, v97
	v_cvt_pk_bf16_f32 v113, v98, v99
	s_waitcnt lgkmcnt(6)
	v_mfma_f32_32x32x16_bf16 v[16:31], v[224:227], v[124:127], v[16:31]
	ds_read_b128 v[220:223], v209 offset:13344
	v_cvt_pk_bf16_f32 v114, v100, v101
	v_cvt_pk_bf16_f32 v115, v102, v103
	v_exp_f32_e32 v104, v104
	v_exp_f32_e32 v105, v105
	s_waitcnt lgkmcnt(6)
	v_mfma_f32_32x32x16_bf16 v[32:47], v[128:131], v[124:127], v[32:47]
	ds_read_b128 v[224:227], v209 offset:17952
	v_exp_f32_e32 v106, v106
	v_exp_f32_e32 v107, v107
	v_exp_f32_e32 v108, v108
	s_waitcnt lgkmcnt(6)
	v_mfma_f32_32x32x16_bf16 v[80:95], v[132:135], v[152:155], v[80:95]
	v_exp_f32_e32 v109, v109
	v_exp_f32_e32 v110, v110
	v_exp_f32_e32 v111, v111
	s_waitcnt lgkmcnt(5)
	v_mfma_f32_32x32x16_bf16 v[80:95], v[136:139], v[156:159], v[80:95]
	v_cvt_pk_bf16_f32 v116, v104, v105
	v_cvt_pk_bf16_f32 v117, v106, v107
	v_cvt_pk_bf16_f32 v118, v108, v109
	v_cvt_pk_bf16_f32 v119, v110, v111
	s_waitcnt lgkmcnt(4)
	v_mfma_f32_32x32x16_bf16 v[80:95], v[140:143], v[160:163], v[80:95]
	v_add_f32_e32 v63, v79, v63
	v_add_f32_e32 v231, v231, v63
	s_waitcnt lgkmcnt(4)
	s_barrier
	ds_read_b128 v[128:131], v187 offset:22528
	ds_read_b128 v[132:135], v187 offset:22560
	ds_read_b128 v[136:139], v187 offset:22592
	s_waitcnt lgkmcnt(6)
	v_mfma_f32_32x32x16_bf16 v[16:31], v[188:191], v[112:115], v[16:31]
	ds_read_b128 v[140:143], v187 offset:22624
	s_waitcnt vmcnt(0)
	ds_write_b128 v211, v[176:179] offset:45056
	s_and_saveexec_b64 s[42:43], s[36:37]
	s_cbranch_execz .Lattn_fx_w6
	ds_write_b128 v186, v[172:175] offset:45056
.Lattn_fx_w6:
	s_or_b64 exec, exec, s[42:43]
	ds_write_b128 v208, v[180:183] offset:58368
	v_exp_f32_e32 v80, v80
	v_exp_f32_e32 v81, v81
	v_exp_f32_e32 v82, v82
	s_waitcnt lgkmcnt(8)
	v_mfma_f32_32x32x16_bf16 v[32:47], v[168:171], v[112:115], v[32:47]
	ds_read_b128 v[188:191], v187 offset:22656
	global_load_dwordx4 v[176:179], v212, s[6:7]
	s_and_saveexec_b64 s[42:43], s[36:37]
	s_cbranch_execz .Lattn_fx_g7
	global_load_dwordx4 v[172:175], v214, s[6:7]
.Lattn_fx_g7:
	s_or_b64 exec, exec, s[42:43]
	global_load_dwordx4 v[180:183], v204, s[40:41]
	s_add_u32 s6, s6, 0x18000
	s_addc_u32 s7, s7, 0
	s_add_u32 s40, s40, 0x80
	s_addc_u32 s41, s41, 0
	v_exp_f32_e32 v83, v83
	v_exp_f32_e32 v84, v84
	v_exp_f32_e32 v85, v85
	s_waitcnt lgkmcnt(8)
	v_mfma_f32_32x32x16_bf16 v[16:31], v[220:223], v[116:119], v[16:31]
	ds_read_b128 v[168:171], v187 offset:22688
	v_exp_f32_e32 v86, v86
	v_exp_f32_e32 v87, v87
	v_cvt_pk_bf16_f32 v120, v80, v81
	v_cvt_pk_bf16_f32 v121, v82, v83
	s_waitcnt lgkmcnt(8)
	v_mfma_f32_32x32x16_bf16 v[32:47], v[224:227], v[116:119], v[32:47]
	ds_read_b128 v[220:223], v209 offset:13376
	v_cvt_pk_bf16_f32 v122, v84, v85
	v_cvt_pk_bf16_f32 v123, v86, v87
	v_exp_f32_e32 v88, v88
	v_exp_f32_e32 v89, v89
	s_waitcnt lgkmcnt(8)
	v_mfma_f32_32x32x16_bf16 v[64:79], v[128:131], v[164:167], v[0:15]
	ds_read_b128 v[224:227], v209 offset:17984
	v_exp_f32_e32 v90, v90
	v_exp_f32_e32 v91, v91
	v_add_f32_e32 v80, v96, v80
	v_add_f32_e32 v244, v244, v80
	s_waitcnt lgkmcnt(8)
	v_mfma_f32_32x32x16_bf16 v[64:79], v[132:135], v[144:147], v[64:79]
	ds_read_b128 v[128:131], v187 offset:29184
	v_exp_f32_e32 v92, v92
	v_exp_f32_e32 v93, v93
	v_add_f32_e32 v81, v97, v81
	v_add_f32_e32 v245, v245, v81
	s_waitcnt lgkmcnt(8)
	v_mfma_f32_32x32x16_bf16 v[64:79], v[136:139], v[148:151], v[64:79]
	ds_read_b128 v[132:135], v187 offset:29216
	v_exp_f32_e32 v94, v94
	v_exp_f32_e32 v95, v95
	v_add_f32_e32 v82, v98, v82
	v_add_f32_e32 v242, v242, v82
	s_waitcnt lgkmcnt(8)
	v_mfma_f32_32x32x16_bf16 v[64:79], v[140:143], v[152:155], v[64:79]
	ds_read_b128 v[136:139], v187 offset:29248
	v_cvt_pk_bf16_f32 v124, v88, v89
	v_cvt_pk_bf16_f32 v125, v90, v91
	v_cvt_pk_bf16_f32 v126, v92, v93
	v_cvt_pk_bf16_f32 v127, v94, v95
	v_add_f32_e32 v83, v99, v83
	v_add_f32_e32 v243, v243, v83
	s_waitcnt lgkmcnt(6)
	v_mfma_f32_32x32x16_bf16 v[64:79], v[188:191], v[156:159], v[64:79]
	ds_read_b128 v[140:143], v209 offset:13408
	v_add_f32_e32 v84, v100, v84
	v_add_f32_e32 v240, v240, v84
	v_add_f32_e32 v85, v101, v85
	v_add_f32_e32 v241, v241, v85
	v_add_f32_e32 v86, v102, v86
	v_add_f32_e32 v238, v238, v86
	s_waitcnt lgkmcnt(6)
	v_mfma_f32_32x32x16_bf16 v[64:79], v[168:171], v[160:163], v[64:79]
	ds_read_b128 v[188:191], v209 offset:18016
	v_add_f32_e32 v87, v103, v87
	v_add_f32_e32 v239, v239, v87
	v_add_f32_e32 v88, v104, v88
	v_add_f32_e32 v236, v236, v88
	v_add_f32_e32 v89, v105, v89
	v_add_f32_e32 v237, v237, v89
	s_waitcnt lgkmcnt(6)
	v_mfma_f32_32x32x16_bf16 v[16:31], v[220:223], v[120:123], v[16:31]
	ds_read_b128 v[168:171], v187 offset:29280
	v_add_f32_e32 v90, v106, v90
	v_add_f32_e32 v234, v234, v90
	v_add_f32_e32 v91, v107, v91
	v_add_f32_e32 v235, v235, v91
	v_add_f32_e32 v92, v108, v92
	v_add_f32_e32 v232, v232, v92
	s_waitcnt lgkmcnt(6)
	v_mfma_f32_32x32x16_bf16 v[32:47], v[224:227], v[120:123], v[32:47]
	ds_read_b128 v[220:223], v187 offset:29312
	v_add_f32_e32 v93, v109, v93
	v_add_f32_e32 v233, v233, v93
	v_add_f32_e32 v94, v110, v94
	v_add_f32_e32 v230, v230, v94
	s_waitcnt lgkmcnt(6)
	v_mfma_f32_32x32x16_bf16 v[48:63], v[128:131], v[164:167], v[0:15]
	ds_read_b128 v[224:227], v187 offset:29344
	v_exp_f32_e32 v64, v64
	v_exp_f32_e32 v65, v65
	v_exp_f32_e32 v66, v66
	s_waitcnt lgkmcnt(6)
	v_mfma_f32_32x32x16_bf16 v[48:63], v[132:135], v[144:147], v[48:63]
	ds_read_b128 v[128:131], v209 offset:35840
	v_exp_f32_e32 v67, v67
	v_exp_f32_e32 v68, v68
	v_exp_f32_e32 v69, v69
	s_waitcnt lgkmcnt(6)
	v_mfma_f32_32x32x16_bf16 v[48:63], v[136:139], v[148:151], v[48:63]
	ds_read_b128 v[132:135], v209 offset:40448
	v_exp_f32_e32 v70, v70
	v_exp_f32_e32 v71, v71
	v_cvt_pk_bf16_f32 v112, v64, v65
	v_cvt_pk_bf16_f32 v113, v66, v67
	s_waitcnt lgkmcnt(6)
	v_mfma_f32_32x32x16_bf16 v[16:31], v[140:143], v[124:127], v[16:31]
	ds_read_b128 v[136:139], v209 offset:35872
	v_cvt_pk_bf16_f32 v114, v68, v69
	v_cvt_pk_bf16_f32 v115, v70, v71
	v_exp_f32_e32 v72, v72
	v_exp_f32_e32 v73, v73
	s_waitcnt lgkmcnt(6)
	v_mfma_f32_32x32x16_bf16 v[32:47], v[188:191], v[124:127], v[32:47]
	ds_read_b128 v[140:143], v209 offset:40480
	v_exp_f32_e32 v74, v74
	v_exp_f32_e32 v75, v75
	v_exp_f32_e32 v76, v76
	s_waitcnt lgkmcnt(6)
	v_mfma_f32_32x32x16_bf16 v[48:63], v[168:171], v[152:155], v[48:63]
	v_exp_f32_e32 v77, v77
	v_exp_f32_e32 v78, v78
	v_exp_f32_e32 v79, v79
	s_waitcnt lgkmcnt(5)
	v_mfma_f32_32x32x16_bf16 v[48:63], v[220:223], v[156:159], v[48:63]
	v_cvt_pk_bf16_f32 v116, v72, v73
	v_cvt_pk_bf16_f32 v117, v74, v75
	v_cvt_pk_bf16_f32 v118, v76, v77
	v_cvt_pk_bf16_f32 v119, v78, v79
	s_waitcnt lgkmcnt(4)
	v_mfma_f32_32x32x16_bf16 v[48:63], v[224:227], v[160:163], v[48:63]
	v_add_f32_e32 v95, v111, v95
	v_add_f32_e32 v231, v231, v95
	s_waitcnt lgkmcnt(4)
	s_barrier
	ds_read_b128 v[188:191], v187 offset:45056
	ds_read_b128 v[168:171], v187 offset:45088
	ds_read_b128 v[220:223], v187 offset:45120
	s_waitcnt lgkmcnt(6)
	v_mfma_f32_32x32x16_bf16 v[16:31], v[128:131], v[112:115], v[16:31]
	ds_read_b128 v[224:227], v187 offset:45152
	s_waitcnt vmcnt(0)
	ds_write_b128 v211, v[176:179] offset:0
	s_and_saveexec_b64 s[42:43], s[36:37]
	s_cbranch_execz .Lattn_fx_w8
	ds_write_b128 v186, v[172:175] offset:0
.Lattn_fx_w8:
	s_or_b64 exec, exec, s[42:43]
	ds_write_b128 v208, v[180:183] offset:13312
	v_exp_f32_e32 v48, v48
	v_exp_f32_e32 v49, v49
	v_exp_f32_e32 v50, v50
	s_waitcnt lgkmcnt(8)
	v_mfma_f32_32x32x16_bf16 v[32:47], v[132:135], v[112:115], v[32:47]
	ds_read_b128 v[128:131], v187 offset:45184
	global_load_dwordx4 v[176:179], v212, s[6:7]
	s_and_saveexec_b64 s[42:43], s[36:37]
	s_cbranch_execz .Lattn_fx_g9
	global_load_dwordx4 v[172:175], v214, s[6:7]
.Lattn_fx_g9:
	s_or_b64 exec, exec, s[42:43]
	global_load_dwordx4 v[180:183], v204, s[40:41]
	s_add_u32 s6, s6, 0x18000
	s_addc_u32 s7, s7, 0
	s_add_u32 s40, s40, 0x80
	s_addc_u32 s41, s41, 0
	v_exp_f32_e32 v51, v51
	v_exp_f32_e32 v52, v52
	v_exp_f32_e32 v53, v53
	s_waitcnt lgkmcnt(8)
	v_mfma_f32_32x32x16_bf16 v[16:31], v[136:139], v[116:119], v[16:31]
	ds_read_b128 v[132:135], v187 offset:45216
	v_exp_f32_e32 v54, v54
	v_exp_f32_e32 v55, v55
	v_cvt_pk_bf16_f32 v120, v48, v49
	v_cvt_pk_bf16_f32 v121, v50, v51
	s_waitcnt lgkmcnt(8)
	v_mfma_f32_32x32x16_bf16 v[32:47], v[140:143], v[116:119], v[32:47]
	ds_read_b128 v[136:139], v209 offset:35904
	v_cvt_pk_bf16_f32 v122, v52, v53
	v_cvt_pk_bf16_f32 v123, v54, v55
	v_exp_f32_e32 v56, v56
	v_exp_f32_e32 v57, v57
	s_waitcnt lgkmcnt(8)
	v_mfma_f32_32x32x16_bf16 v[96:111], v[188:191], v[164:167], v[0:15]
	ds_read_b128 v[140:143], v209 offset:40512
	v_exp_f32_e32 v58, v58
	v_exp_f32_e32 v59, v59
	v_add_f32_e32 v48, v64, v48
	v_add_f32_e32 v244, v244, v48
	s_waitcnt lgkmcnt(8)
	v_mfma_f32_32x32x16_bf16 v[96:111], v[168:171], v[144:147], v[96:111]
	ds_read_b128 v[188:191], v187 offset:51712
	v_exp_f32_e32 v60, v60
	v_exp_f32_e32 v61, v61
	v_add_f32_e32 v49, v65, v49
	v_add_f32_e32 v245, v245, v49
	s_waitcnt lgkmcnt(8)
	v_mfma_f32_32x32x16_bf16 v[96:111], v[220:223], v[148:151], v[96:111]
	ds_read_b128 v[168:171], v187 offset:51744
	v_exp_f32_e32 v62, v62
	v_exp_f32_e32 v63, v63
	v_add_f32_e32 v50, v66, v50
	v_add_f32_e32 v242, v242, v50
	s_waitcnt lgkmcnt(8)
	v_mfma_f32_32x32x16_bf16 v[96:111], v[224:227], v[152:155], v[96:111]
	ds_read_b128 v[220:223], v187 offset:51776
	v_cvt_pk_bf16_f32 v124, v56, v57
	v_cvt_pk_bf16_f32 v125, v58, v59
	v_cvt_pk_bf16_f32 v126, v60, v61
	v_cvt_pk_bf16_f32 v127, v62, v63
	v_add_f32_e32 v51, v67, v51
	v_add_f32_e32 v243, v243, v51
	s_waitcnt lgkmcnt(6)
	v_mfma_f32_32x32x16_bf16 v[96:111], v[128:131], v[156:159], v[96:111]
	ds_read_b128 v[224:227], v209 offset:35936
	v_add_f32_e32 v52, v68, v52
	v_add_f32_e32 v240, v240, v52
	v_add_f32_e32 v53, v69, v53
	v_add_f32_e32 v241, v241, v53
	v_add_f32_e32 v54, v70, v54
	v_add_f32_e32 v238, v238, v54
	s_waitcnt lgkmcnt(6)
	v_mfma_f32_32x32x16_bf16 v[96:111], v[132:135], v[160:163], v[96:111]
	ds_read_b128 v[128:131], v209 offset:40544
	v_add_f32_e32 v55, v71, v55
	v_add_f32_e32 v239, v239, v55
	v_add_f32_e32 v56, v72, v56
	v_add_f32_e32 v236, v236, v56
	v_add_f32_e32 v57, v73, v57
	v_add_f32_e32 v237, v237, v57
	s_waitcnt lgkmcnt(6)
	v_mfma_f32_32x32x16_bf16 v[16:31], v[136:139], v[120:123], v[16:31]
	ds_read_b128 v[132:135], v187 offset:51808
	v_add_f32_e32 v58, v74, v58
	v_add_f32_e32 v234, v234, v58
	v_add_f32_e32 v59, v75, v59
	v_add_f32_e32 v235, v235, v59
	v_add_f32_e32 v60, v76, v60
	v_add_f32_e32 v232, v232, v60
	s_waitcnt lgkmcnt(6)
	v_mfma_f32_32x32x16_bf16 v[32:47], v[140:143], v[120:123], v[32:47]
	ds_read_b128 v[136:139], v187 offset:51840
	v_add_f32_e32 v61, v77, v61
	v_add_f32_e32 v233, v233, v61
	v_add_f32_e32 v62, v78, v62
	v_add_f32_e32 v230, v230, v62
	s_waitcnt lgkmcnt(6)
	v_mfma_f32_32x32x16_bf16 v[80:95], v[188:191], v[164:167], v[0:15]
	ds_read_b128 v[140:143], v187 offset:51872
	v_exp_f32_e32 v96, v96
	v_exp_f32_e32 v97, v97
	v_exp_f32_e32 v98, v98
	s_waitcnt lgkmcnt(6)
	v_mfma_f32_32x32x16_bf16 v[80:95], v[168:171], v[144:147], v[80:95]
	ds_read_b128 v[188:191], v209 offset:58368
	v_exp_f32_e32 v99, v99
	v_exp_f32_e32 v100, v100
	v_exp_f32_e32 v101, v101
	s_waitcnt lgkmcnt(6)
	v_mfma_f32_32x32x16_bf16 v[80:95], v[220:223], v[148:151], v[80:95]
	ds_read_b128 v[168:171], v209 offset:62976
	v_exp_f32_e32 v102, v102
	v_exp_f32_e32 v103, v103
	v_cvt_pk_bf16_f32 v112, v96, v97
	v_cvt_pk_bf16_f32 v113, v98, v99
	s_waitcnt lgkmcnt(6)
	v_mfma_f32_32x32x16_bf16 v[16:31], v[224:227], v[124:127], v[16:31]
	ds_read_b128 v[220:223], v209 offset:58400
	v_cvt_pk_bf16_f32 v114, v100, v101
	v_cvt_pk_bf16_f32 v115, v102, v103
	v_exp_f32_e32 v104, v104
	v_exp_f32_e32 v105, v105
	s_waitcnt lgkmcnt(6)
	v_mfma_f32_32x32x16_bf16 v[32:47], v[128:131], v[124:127], v[32:47]
	ds_read_b128 v[224:227], v209 offset:63008
	v_exp_f32_e32 v106, v106
	v_exp_f32_e32 v107, v107
	v_exp_f32_e32 v108, v108
	s_waitcnt lgkmcnt(6)
	v_mfma_f32_32x32x16_bf16 v[80:95], v[132:135], v[152:155], v[80:95]
	v_exp_f32_e32 v109, v109
	v_exp_f32_e32 v110, v110
	v_exp_f32_e32 v111, v111
	s_waitcnt lgkmcnt(5)
	v_mfma_f32_32x32x16_bf16 v[80:95], v[136:139], v[156:159], v[80:95]
	v_cvt_pk_bf16_f32 v116, v104, v105
	v_cvt_pk_bf16_f32 v117, v106, v107
	v_cvt_pk_bf16_f32 v118, v108, v109
	v_cvt_pk_bf16_f32 v119, v110, v111
	s_waitcnt lgkmcnt(4)
	v_mfma_f32_32x32x16_bf16 v[80:95], v[140:143], v[160:163], v[80:95]
	v_add_f32_e32 v63, v79, v63
	v_add_f32_e32 v231, v231, v63
	s_waitcnt lgkmcnt(4)
	s_barrier
	ds_read_b128 v[128:131], v187 offset:0
	ds_read_b128 v[132:135], v187 offset:32
	ds_read_b128 v[136:139], v187 offset:64
	s_waitcnt lgkmcnt(6)
	v_mfma_f32_32x32x16_bf16 v[16:31], v[188:191], v[112:115], v[16:31]
	ds_read_b128 v[140:143], v187 offset:96
	s_waitcnt vmcnt(0)
	ds_write_b128 v211, v[176:179] offset:22528
	s_and_saveexec_b64 s[42:43], s[36:37]
	s_cbranch_execz .Lattn_fx_w10
	ds_write_b128 v186, v[172:175] offset:22528
.Lattn_fx_w10:
	s_or_b64 exec, exec, s[42:43]
	ds_write_b128 v208, v[180:183] offset:35840
	v_exp_f32_e32 v80, v80
	v_exp_f32_e32 v81, v81
	v_exp_f32_e32 v82, v82
	s_waitcnt lgkmcnt(8)
	v_mfma_f32_32x32x16_bf16 v[32:47], v[168:171], v[112:115], v[32:47]
	ds_read_b128 v[188:191], v187 offset:128
	s_cmp_eq_u32 s14, 20
	s_cbranch_scc1 .Lattn_fx_skipld
	global_load_dwordx4 v[176:179], v212, s[6:7]
	s_and_saveexec_b64 s[42:43], s[36:37]
	s_cbranch_execz .Lattn_fx_g11
	global_load_dwordx4 v[172:175], v214, s[6:7]

; template <bool FIXED> __device__ __forceinline__ void attn_unit(unsigned char* ws, LAS unsigned char* lds, int b, int h, int qb, const int tid, const float sbound) {
;     ...
;     if constexpr (FIXED) { for (int kt = 0; kt < SEQ / 64; kt += 2) { ATT_STEP_FIXED(pA0, pA1, pB0, pB1, kt); ATT_STEP_FIXED(pB0, pB1, pA0, pA1, kt + 1); }
.Lattn_fx_skipld:
	v_exp_f32_e32 v83, v83
	v_exp_f32_e32 v84, v84
	v_exp_f32_e32 v85, v85
	s_waitcnt lgkmcnt(8)
	v_mfma_f32_32x32x16_bf16 v[16:31], v[220:223], v[116:119], v[16:31]
	ds_read_b128 v[168:171], v187 offset:160
	v_exp_f32_e32 v86, v86
	v_exp_f32_e32 v87, v87
	v_cvt_pk_bf16_f32 v120, v80, v81
	v_cvt_pk_bf16_f32 v121, v82, v83
	s_waitcnt lgkmcnt(8)
	v_mfma_f32_32x32x16_bf16 v[32:47], v[224:227], v[116:119], v[32:47]
	ds_read_b128 v[220:223], v209 offset:58432
	v_cvt_pk_bf16_f32 v122, v84, v85
	v_cvt_pk_bf16_f32 v123, v86, v87
	v_exp_f32_e32 v88, v88
	v_exp_f32_e32 v89, v89
	s_waitcnt lgkmcnt(8)
	v_mfma_f32_32x32x16_bf16 v[64:79], v[128:131], v[164:167], v[0:15]
	ds_read_b128 v[224:227], v209 offset:63040
	v_exp_f32_e32 v90, v90
	v_exp_f32_e32 v91, v91
	v_add_f32_e32 v80, v96, v80
	v_add_f32_e32 v244, v244, v80
	s_waitcnt lgkmcnt(8)
	v_mfma_f32_32x32x16_bf16 v[64:79], v[132:135], v[144:147], v[64:79]
	ds_read_b128 v[128:131], v187 offset:6656
	v_exp_f32_e32 v92, v92
	v_exp_f32_e32 v93, v93
	v_add_f32_e32 v81, v97, v81
	v_add_f32_e32 v245, v245, v81
	s_waitcnt lgkmcnt(8)
	v_mfma_f32_32x32x16_bf16 v[64:79], v[136:139], v[148:151], v[64:79]
	ds_read_b128 v[132:135], v187 offset:6688
	v_exp_f32_e32 v94, v94
	v_exp_f32_e32 v95, v95
	v_add_f32_e32 v82, v98, v82
	v_add_f32_e32 v242, v242, v82
	s_waitcnt lgkmcnt(8)
	v_mfma_f32_32x32x16_bf16 v[64:79], v[140:143], v[152:155], v[64:79]
	ds_read_b128 v[136:139], v187 offset:6720
	v_cvt_pk_bf16_f32 v124, v88, v89
	v_cvt_pk_bf16_f32 v125, v90, v91
	v_cvt_pk_bf16_f32 v126, v92, v93
	v_cvt_pk_bf16_f32 v127, v94, v95
	v_add_f32_e32 v83, v99, v83
	v_add_f32_e32 v243, v243, v83
	s_waitcnt lgkmcnt(6)
	v_mfma_f32_32x32x16_bf16 v[64:79], v[188:191], v[156:159], v[64:79]
	ds_read_b128 v[140:143], v209 offset:58464
	v_add_f32_e32 v84, v100, v84
	v_add_f32_e32 v240, v240, v84
	v_add_f32_e32 v85, v101, v85
	v_add_f32_e32 v241, v241, v85
	v_add_f32_e32 v86, v102, v86
	v_add_f32_e32 v238, v238, v86
	s_waitcnt lgkmcnt(6)
	v_mfma_f32_32x32x16_bf16 v[64:79], v[168:171], v[160:163], v[64:79]
	ds_read_b128 v[188:191], v209 offset:63072
	v_add_f32_e32 v87, v103, v87
	v_add_f32_e32 v239, v239, v87
	v_add_f32_e32 v88, v104, v88
	v_add_f32_e32 v236, v236, v88
	v_add_f32_e32 v89, v105, v89
	v_add_f32_e32 v237, v237, v89
	s_waitcnt lgkmcnt(6)
	v_mfma_f32_32x32x16_bf16 v[16:31], v[220:223], v[120:123], v[16:31]
	ds_read_b128 v[168:171], v187 offset:6752
	v_add_f32_e32 v90, v106, v90
	v_add_f32_e32 v234, v234, v90
	v_add_f32_e32 v91, v107, v91
	v_add_f32_e32 v235, v235, v91
	v_add_f32_e32 v92, v108, v92
	v_add_f32_e32 v232, v232, v92
	s_waitcnt lgkmcnt(6)
	v_mfma_f32_32x32x16_bf16 v[32:47], v[224:227], v[120:123], v[32:47]
	ds_read_b128 v[220:223], v187 offset:6784
	v_add_f32_e32 v93, v109, v93
	v_add_f32_e32 v233, v233, v93
	v_add_f32_e32 v94, v110, v94
	v_add_f32_e32 v230, v230, v94
	s_waitcnt lgkmcnt(6)
	v_mfma_f32_32x32x16_bf16 v[48:63], v[128:131], v[164:167], v[0:15]
	ds_read_b128 v[224:227], v187 offset:6816
	v_exp_f32_e32 v64, v64
	v_exp_f32_e32 v65, v65
	v_exp_f32_e32 v66, v66
	s_waitcnt lgkmcnt(6)
	v_mfma_f32_32x32x16_bf16 v[48:63], v[132:135], v[144:147], v[48:63]
	ds_read_b128 v[128:131], v209 offset:13312
	v_exp_f32_e32 v67, v67
	v_exp_f32_e32 v68, v68
	v_exp_f32_e32 v69, v69
	s_waitcnt lgkmcnt(6)
	v_mfma_f32_32x32x16_bf16 v[48:63], v[136:139], v[148:151], v[48:63]
	ds_read_b128 v[132:135], v209 offset:17920
	v_exp_f32_e32 v70, v70
	v_exp_f32_e32 v71, v71
	v_cvt_pk_bf16_f32 v112, v64, v65
	v_cvt_pk_bf16_f32 v113, v66, v67
	s_waitcnt lgkmcnt(6)
	v_mfma_f32_32x32x16_bf16 v[16:31], v[140:143], v[124:127], v[16:31]
	ds_read_b128 v[136:139], v209 offset:13344
	v_cvt_pk_bf16_f32 v114, v68, v69
	v_cvt_pk_bf16_f32 v115, v70, v71
	v_exp_f32_e32 v72, v72
	v_exp_f32_e32 v73, v73
	s_waitcnt lgkmcnt(6)
	v_mfma_f32_32x32x16_bf16 v[32:47], v[188:191], v[124:127], v[32:47]
	ds_read_b128 v[140:143], v209 offset:17952
	v_exp_f32_e32 v74, v74
	v_exp_f32_e32 v75, v75
	v_exp_f32_e32 v76, v76
	s_waitcnt lgkmcnt(6)
	v_mfma_f32_32x32x16_bf16 v[48:63], v[168:171], v[152:155], v[48:63]
	v_exp_f32_e32 v77, v77
	v_exp_f32_e32 v78, v78
	v_exp_f32_e32 v79, v79
	s_waitcnt lgkmcnt(5)
	v_mfma_f32_32x32x16_bf16 v[48:63], v[220:223], v[156:159], v[48:63]
	v_cvt_pk_bf16_f32 v116, v72, v73
	v_cvt_pk_bf16_f32 v117, v74, v75
	v_cvt_pk_bf16_f32 v118, v76, v77
	v_cvt_pk_bf16_f32 v119, v78, v79
	s_waitcnt lgkmcnt(4)
	v_mfma_f32_32x32x16_bf16 v[48:63], v[224:227], v[160:163], v[48:63]
	v_add_f32_e32 v95, v111, v95
	v_add_f32_e32 v231, v231, v95
	s_waitcnt lgkmcnt(4)
	s_barrier
	s_add_i32 s14, s14, 1
	s_cmp_lt_u32 s14, 21
	s_cbranch_scc1 .Lattn_fx_loop
	ds_read_b128 v[188:191], v187 offset:22528
	ds_read_b128 v[168:171], v187 offset:22560
	ds_read_b128 v[220:223], v187 offset:22592
	s_waitcnt lgkmcnt(6)
	v_mfma_f32_32x32x16_bf16 v[16:31], v[128:131], v[112:115], v[16:31]
	ds_read_b128 v[224:227], v187 offset:22624
	s_nop 7
	v_exp_f32_e32 v48, v48
	v_exp_f32_e32 v49, v49
	v_exp_f32_e32 v50, v50
	s_waitcnt lgkmcnt(6)
	v_mfma_f32_32x32x16_bf16 v[32:47], v[132:135], v[112:115], v[32:47]
	ds_read_b128 v[128:131], v187 offset:22656
	v_exp_f32_e32 v51, v51
	v_exp_f32_e32 v52, v52
	v_exp_f32_e32 v53, v53
	s_waitcnt lgkmcnt(6)
	v_mfma_f32_32x32x16_bf16 v[16:31], v[136:139], v[116:119], v[16:31]
	ds_read_b128 v[132:135], v187 offset:22688
	v_exp_f32_e32 v54, v54
	v_exp_f32_e32 v55, v55
	v_cvt_pk_bf16_f32 v120, v48, v49
	v_cvt_pk_bf16_f32 v121, v50, v51
	s_waitcnt lgkmcnt(6)
	v_mfma_f32_32x32x16_bf16 v[32:47], v[140:143], v[116:119], v[32:47]
	ds_read_b128 v[136:139], v209 offset:13376
	v_cvt_pk_bf16_f32 v122, v52, v53
	v_cvt_pk_bf16_f32 v123, v54, v55
	v_exp_f32_e32 v56, v56
	v_exp_f32_e32 v57, v57
	s_waitcnt lgkmcnt(6)
	v_mfma_f32_32x32x16_bf16 v[96:111], v[188:191], v[164:167], v[0:15]
	ds_read_b128 v[140:143], v209 offset:17984
	v_exp_f32_e32 v58, v58
	v_exp_f32_e32 v59, v59
	v_add_f32_e32 v48, v64, v48
	v_add_f32_e32 v244, v244, v48
	s_waitcnt lgkmcnt(6)
	v_mfma_f32_32x32x16_bf16 v[96:111], v[168:171], v[144:147], v[96:111]
	ds_read_b128 v[188:191], v187 offset:29184
	v_exp_f32_e32 v60, v60
	v_exp_f32_e32 v61, v61
	v_add_f32_e32 v49, v65, v49
	v_add_f32_e32 v245, v245, v49
	s_waitcnt lgkmcnt(6)
	v_mfma_f32_32x32x16_bf16 v[96:111], v[220:223], v[148:151], v[96:111]
	ds_read_b128 v[168:171], v187 offset:29216
	v_exp_f32_e32 v62, v62
	v_exp_f32_e32 v63, v63
	v_add_f32_e32 v50, v66, v50
	v_add_f32_e32 v242, v242, v50
	s_waitcnt lgkmcnt(6)
	v_mfma_f32_32x32x16_bf16 v[96:111], v[224:227], v[152:155], v[96:111]
	ds_read_b128 v[220:223], v187 offset:29248
	v_cvt_pk_bf16_f32 v124, v56, v57
	v_cvt_pk_bf16_f32 v125, v58, v59
	v_cvt_pk_bf16_f32 v126, v60, v61
	v_cvt_pk_bf16_f32 v127, v62, v63
	v_add_f32_e32 v51, v67, v51
	v_add_f32_e32 v243, v243, v51
	s_waitcnt lgkmcnt(6)
	v_mfma_f32_32x32x16_bf16 v[96:111], v[128:131], v[156:159], v[96:111]
	ds_read_b128 v[224:227], v209 offset:13408
	v_add_f32_e32 v52, v68, v52
	v_add_f32_e32 v240, v240, v52
	v_add_f32_e32 v53, v69, v53
	v_add_f32_e32 v241, v241, v53
	v_add_f32_e32 v54, v70, v54
	v_add_f32_e32 v238, v238, v54
	s_waitcnt lgkmcnt(6)
	v_mfma_f32_32x32x16_bf16 v[96:111], v[132:135], v[160:163], v[96:111]
	ds_read_b128 v[128:131], v209 offset:18016
	v_add_f32_e32 v55, v71, v55
	v_add_f32_e32 v239, v239, v55
	v_add_f32_e32 v56, v72, v56
	v_add_f32_e32 v236, v236, v56
	v_add_f32_e32 v57, v73, v57
	v_add_f32_e32 v237, v237, v57
	s_waitcnt lgkmcnt(6)
	v_mfma_f32_32x32x16_bf16 v[16:31], v[136:139], v[120:123], v[16:31]
	ds_read_b128 v[132:135], v187 offset:29280
	v_add_f32_e32 v58, v74, v58
	v_add_f32_e32 v234, v234, v58
	v_add_f32_e32 v59, v75, v59
	v_add_f32_e32 v235, v235, v59
	v_add_f32_e32 v60, v76, v60
	v_add_f32_e32 v232, v232, v60
	s_waitcnt lgkmcnt(6)
	v_mfma_f32_32x32x16_bf16 v[32:47], v[140:143], v[120:123], v[32:47]
	ds_read_b128 v[136:139], v187 offset:29312
	v_add_f32_e32 v61, v77, v61
	v_add_f32_e32 v233, v233, v61
	v_add_f32_e32 v62, v78, v62
	v_add_f32_e32 v230, v230, v62
	s_waitcnt lgkmcnt(6)
	v_mfma_f32_32x32x16_bf16 v[80:95], v[188:191], v[164:167], v[0:15]
	ds_read_b128 v[140:143], v187 offset:29344
	v_exp_f32_e32 v96, v96
	v_exp_f32_e32 v97, v97
	v_exp_f32_e32 v98, v98
	s_waitcnt lgkmcnt(6)
	v_mfma_f32_32x32x16_bf16 v[80:95], v[168:171], v[144:147], v[80:95]
	ds_read_b128 v[188:191], v209 offset:35840
	v_exp_f32_e32 v99, v99
	v_exp_f32_e32 v100, v100
	v_exp_f32_e32 v101, v101
	s_waitcnt lgkmcnt(6)
	v_mfma_f32_32x32x16_bf16 v[80:95], v[220:223], v[148:151], v[80:95]
	ds_read_b128 v[168:171], v209 offset:40448
	v_exp_f32_e32 v102, v102
	v_exp_f32_e32 v103, v103
	v_cvt_pk_bf16_f32 v112, v96, v97
	v_cvt_pk_bf16_f32 v113, v98, v99
	s_waitcnt lgkmcnt(6)
	v_mfma_f32_32x32x16_bf16 v[16:31], v[224:227], v[124:127], v[16:31]
	ds_read_b128 v[220:223], v209 offset:35872
	v_cvt_pk_bf16_f32 v114, v100, v101
	v_cvt_pk_bf16_f32 v115, v102, v103
	v_exp_f32_e32 v104, v104
	v_exp_f32_e32 v105, v105
	s_waitcnt lgkmcnt(6)
	v_mfma_f32_32x32x16_bf16 v[32:47], v[128:131], v[124:127], v[32:47]
	ds_read_b128 v[224:227], v209 offset:40480
	v_exp_f32_e32 v106, v106
	v_exp_f32_e32 v107, v107
	v_exp_f32_e32 v108, v108
	s_waitcnt lgkmcnt(6)
	v_mfma_f32_32x32x16_bf16 v[80:95], v[132:135], v[152:155], v[80:95]
	v_exp_f32_e32 v109, v109
	v_exp_f32_e32 v110, v110
	v_exp_f32_e32 v111, v111
	s_waitcnt lgkmcnt(5)
	v_mfma_f32_32x32x16_bf16 v[80:95], v[136:139], v[156:159], v[80:95]
	v_cvt_pk_bf16_f32 v116, v104, v105
	v_cvt_pk_bf16_f32 v117, v106, v107
	v_cvt_pk_bf16_f32 v118, v108, v109
	v_cvt_pk_bf16_f32 v119, v110, v111
	s_waitcnt lgkmcnt(4)
	v_mfma_f32_32x32x16_bf16 v[80:95], v[140:143], v[160:163], v[80:95]
	v_add_f32_e32 v63, v79, v63
	v_add_f32_e32 v231, v231, v63
	s_waitcnt lgkmcnt(4)
	s_barrier
	ds_read_b128 v[128:131], v209 offset:35904
	ds_read_b128 v[132:135], v209 offset:40512
	ds_read_b128 v[136:139], v209 offset:35936
	s_waitcnt lgkmcnt(6)
	v_mfma_f32_32x32x16_bf16 v[16:31], v[188:191], v[112:115], v[16:31]
	ds_read_b128 v[140:143], v209 offset:40544
	s_nop 7
	v_exp_f32_e32 v80, v80
	v_exp_f32_e32 v81, v81
	v_exp_f32_e32 v82, v82
	v_exp_f32_e32 v83, v83
	v_exp_f32_e32 v84, v84
	v_exp_f32_e32 v85, v85
	v_exp_f32_e32 v86, v86
	v_exp_f32_e32 v87, v87
	s_waitcnt lgkmcnt(6)
	v_mfma_f32_32x32x16_bf16 v[32:47], v[168:171], v[112:115], v[32:47]
	v_cvt_pk_bf16_f32 v120, v80, v81
	v_cvt_pk_bf16_f32 v121, v82, v83
	v_cvt_pk_bf16_f32 v122, v84, v85
	v_cvt_pk_bf16_f32 v123, v86, v87
	v_exp_f32_e32 v88, v88
	v_exp_f32_e32 v89, v89
	v_exp_f32_e32 v90, v90
	v_exp_f32_e32 v91, v91
	s_waitcnt lgkmcnt(5)
	v_mfma_f32_32x32x16_bf16 v[16:31], v[220:223], v[116:119], v[16:31]
	v_exp_f32_e32 v92, v92
	v_exp_f32_e32 v93, v93
	v_exp_f32_e32 v94, v94
	v_exp_f32_e32 v95, v95
	s_waitcnt lgkmcnt(4)
	v_mfma_f32_32x32x16_bf16 v[32:47], v[224:227], v[116:119], v[32:47]
	v_cvt_pk_bf16_f32 v124, v88, v89
	v_cvt_pk_bf16_f32 v125, v90, v91
	v_cvt_pk_bf16_f32 v126, v92, v93
	v_cvt_pk_bf16_f32 v127, v94, v95
	s_waitcnt lgkmcnt(3)
	v_mfma_f32_32x32x16_bf16 v[16:31], v[128:131], v[120:123], v[16:31]
	v_add_f32_e32 v80, v96, v80
	v_add_f32_e32 v244, v244, v80
	v_add_f32_e32 v81, v97, v81
	v_add_f32_e32 v245, v245, v81
	v_add_f32_e32 v82, v98, v82
	v_add_f32_e32 v242, v242, v82
	v_add_f32_e32 v83, v99, v83
	v_add_f32_e32 v243, v243, v83
	s_waitcnt lgkmcnt(2)
	v_mfma_f32_32x32x16_bf16 v[32:47], v[132:135], v[120:123], v[32:47]
	v_add_f32_e32 v84, v100, v84
	v_add_f32_e32 v240, v240, v84
	v_add_f32_e32 v85, v101, v85
	v_add_f32_e32 v241, v241, v85
	v_add_f32_e32 v86, v102, v86
	v_add_f32_e32 v238, v238, v86
	v_add_f32_e32 v87, v103, v87
	v_add_f32_e32 v239, v239, v87
	s_waitcnt lgkmcnt(1)
	v_mfma_f32_32x32x16_bf16 v[16:31], v[136:139], v[124:127], v[16:31]
	v_add_f32_e32 v88, v104, v88
	v_add_f32_e32 v236, v236, v88
	v_add_f32_e32 v89, v105, v89
	v_add_f32_e32 v237, v237, v89
	v_add_f32_e32 v90, v106, v90
	v_add_f32_e32 v234, v234, v90
	v_add_f32_e32 v91, v107, v91
	v_add_f32_e32 v235, v235, v91
	s_waitcnt lgkmcnt(0)
	v_mfma_f32_32x32x16_bf16 v[32:47], v[140:143], v[124:127], v[32:47]
	v_add_f32_e32 v92, v108, v92
	v_add_f32_e32 v232, v232, v92
	v_add_f32_e32 v93, v109, v93
	v_add_f32_e32 v233, v233, v93
	v_add_f32_e32 v94, v110, v94
	v_add_f32_e32 v230, v230, v94
	v_add_f32_e32 v95, v111, v95
	v_add_f32_e32 v231, v231, v95
	s_waitcnt lgkmcnt(0)
	s_barrier
